# v24 plus indexer head loop: the 16 packed f32 fma per head split into 32 scalar v_fmac (bit-identical); packed fp32 VALU ops issue far slower than two scalar ops on this chip
# speedup vs baseline: 1.0019x; 1.0019x over previous
.LBB0_615:
	ds_read_b128 v[238:241], v132
	ds_read_b128 v[242:245], v132 offset:16
	ds_read_b128 v[246:249], v132 offset:32
	ds_read_b128 v[250:253], v132 offset:48
	ds_read_b128 v[166:169], v69
	ds_read_b128 v[170:173], v69 offset:32
	ds_read_b128 v[174:177], v69 offset:64
	ds_read_b128 v[178:181], v69 offset:96
	s_setprio 1
	s_waitcnt lgkmcnt(3)
	s_waitcnt vmcnt(7)
	v_mfma_f32_32x32x16_f16 v[2:17], v[34:37], v[166:169], 0
	s_waitcnt vmcnt(5)
	v_mfma_f32_32x32x16_f16 v[18:33], v[42:45], v[166:169], 0
	ds_read_b128 v[166:169], v69 offset:128
	s_waitcnt lgkmcnt(3)
	v_mfma_f32_32x32x16_f16 v[2:17], v[38:41], v[170:173], v[2:17]
	s_waitcnt vmcnt(4)
	v_mfma_f32_32x32x16_f16 v[18:33], v[46:49], v[170:173], v[18:33]
	ds_read_b128 v[170:173], v69 offset:160
	s_waitcnt lgkmcnt(3)
	s_waitcnt vmcnt(3)
	v_mfma_f32_32x32x16_f16 v[2:17], v[50:53], v[174:177], v[2:17]
	s_waitcnt vmcnt(1)
	v_mfma_f32_32x32x16_f16 v[18:33], v[58:61], v[174:177], v[18:33]
	ds_read_b128 v[174:177], v69 offset:192
	s_waitcnt lgkmcnt(3)
	v_mfma_f32_32x32x16_f16 v[2:17], v[54:57], v[178:181], v[2:17]
	s_waitcnt vmcnt(0)
	v_mfma_f32_32x32x16_f16 v[18:33], v[62:65], v[178:181], v[18:33]
	ds_read_b128 v[178:181], v69 offset:224
	s_waitcnt lgkmcnt(3)
	v_mfma_f32_32x32x16_f16 v[182:197], v[34:37], v[166:169], 0
	s_nop 1
	v_max_f32_e32 v2, 0, v2
	v_max_f32_e32 v3, 0, v3
	v_max_f32_e32 v4, 0, v4
	v_max_f32_e32 v5, 0, v5
	v_max_f32_e32 v6, 0, v6
	v_max_f32_e32 v7, 0, v7
	v_max_f32_e32 v8, 0, v8
	v_max_f32_e32 v9, 0, v9
	v_mfma_f32_32x32x16_f16 v[222:237], v[42:45], v[166:169], 0
	ds_read_b128 v[166:169], v69 offset:256
	v_max_f32_e32 v10, 0, v10
	v_max_f32_e32 v11, 0, v11
	v_max_f32_e32 v12, 0, v12
	v_max_f32_e32 v13, 0, v13
	v_max_f32_e32 v14, 0, v14
	v_max_f32_e32 v15, 0, v15
	v_max_f32_e32 v16, 0, v16
	v_max_f32_e32 v17, 0, v17
	s_waitcnt lgkmcnt(3)
	v_mfma_f32_32x32x16_f16 v[182:197], v[38:41], v[170:173], v[182:197]
	v_max_f32_e32 v18, 0, v18
	v_max_f32_e32 v19, 0, v19
	v_max_f32_e32 v20, 0, v20
	v_max_f32_e32 v21, 0, v21
	v_max_f32_e32 v22, 0, v22
	v_max_f32_e32 v23, 0, v23
	v_max_f32_e32 v24, 0, v24
	v_max_f32_e32 v25, 0, v25
	v_mfma_f32_32x32x16_f16 v[222:237], v[46:49], v[170:173], v[222:237]
	ds_read_b128 v[170:173], v69 offset:288
	v_max_f32_e32 v26, 0, v26
	v_max_f32_e32 v27, 0, v27
	v_max_f32_e32 v28, 0, v28
	v_max_f32_e32 v29, 0, v29
	v_max_f32_e32 v30, 0, v30
	v_max_f32_e32 v31, 0, v31
	v_max_f32_e32 v32, 0, v32
	v_max_f32_e32 v33, 0, v33
	s_waitcnt lgkmcnt(3)
	v_mfma_f32_32x32x16_f16 v[182:197], v[50:53], v[174:177], v[182:197]
	v_fmac_f32_e32 v108, v238, v2
	v_fmac_f32_e32 v109, v238, v3
	v_fmac_f32_e32 v110, v238, v4
	v_fmac_f32_e32 v111, v238, v5
	v_fmac_f32_e32 v104, v238, v6
	v_fmac_f32_e32 v105, v238, v7
	v_fmac_f32_e32 v106, v238, v8
	v_fmac_f32_e32 v107, v238, v9
	v_mfma_f32_32x32x16_f16 v[222:237], v[58:61], v[174:177], v[222:237]
	ds_read_b128 v[174:177], v69 offset:320
	v_fmac_f32_e32 v100, v238, v10
	v_fmac_f32_e32 v101, v238, v11
	v_fmac_f32_e32 v102, v238, v12
	v_fmac_f32_e32 v103, v238, v13
	v_fmac_f32_e32 v98, v238, v14
	v_fmac_f32_e32 v99, v238, v15
	v_fmac_f32_e32 v84, v238, v16
	v_fmac_f32_e32 v85, v238, v17
	s_waitcnt lgkmcnt(3)
	v_mfma_f32_32x32x16_f16 v[182:197], v[54:57], v[178:181], v[182:197]
	v_fmac_f32_e32 v94, v238, v18
	v_fmac_f32_e32 v95, v238, v19
	v_fmac_f32_e32 v96, v238, v20
	v_fmac_f32_e32 v97, v238, v21
	v_fmac_f32_e32 v90, v238, v22
	v_fmac_f32_e32 v91, v238, v23
	v_fmac_f32_e32 v92, v238, v24
	v_fmac_f32_e32 v93, v238, v25
	v_mfma_f32_32x32x16_f16 v[222:237], v[62:65], v[178:181], v[222:237]
	ds_read_b128 v[178:181], v69 offset:352
	v_fmac_f32_e32 v86, v238, v26
	v_fmac_f32_e32 v87, v238, v27
	v_fmac_f32_e32 v88, v238, v28
	v_fmac_f32_e32 v89, v238, v29
	v_fmac_f32_e32 v82, v238, v30
	v_fmac_f32_e32 v83, v238, v31
	v_fmac_f32_e32 v78, v238, v32
	v_fmac_f32_e32 v79, v238, v33
	s_waitcnt lgkmcnt(3)
	v_mfma_f32_32x32x16_f16 v[2:17], v[34:37], v[166:169], 0
	s_nop 1
	v_max_f32_e32 v182, 0, v182
	v_max_f32_e32 v183, 0, v183
	v_max_f32_e32 v184, 0, v184
	v_max_f32_e32 v185, 0, v185
	v_max_f32_e32 v186, 0, v186
	v_max_f32_e32 v187, 0, v187
	v_max_f32_e32 v188, 0, v188
	v_max_f32_e32 v189, 0, v189
	v_mfma_f32_32x32x16_f16 v[18:33], v[42:45], v[166:169], 0
	ds_read_b128 v[166:169], v69 offset:384
	v_max_f32_e32 v190, 0, v190
	v_max_f32_e32 v191, 0, v191
	v_max_f32_e32 v192, 0, v192
	v_max_f32_e32 v193, 0, v193
	v_max_f32_e32 v194, 0, v194
	v_max_f32_e32 v195, 0, v195
	v_max_f32_e32 v196, 0, v196
	v_max_f32_e32 v197, 0, v197
	s_waitcnt lgkmcnt(3)
	v_mfma_f32_32x32x16_f16 v[2:17], v[38:41], v[170:173], v[2:17]
	v_max_f32_e32 v222, 0, v222
	v_max_f32_e32 v223, 0, v223
	v_max_f32_e32 v224, 0, v224
	v_max_f32_e32 v225, 0, v225
	v_max_f32_e32 v226, 0, v226
	v_max_f32_e32 v227, 0, v227
	v_max_f32_e32 v228, 0, v228
	v_max_f32_e32 v229, 0, v229
	v_mfma_f32_32x32x16_f16 v[18:33], v[46:49], v[170:173], v[18:33]
	ds_read_b128 v[170:173], v69 offset:416
	v_max_f32_e32 v230, 0, v230
	v_max_f32_e32 v231, 0, v231
	v_max_f32_e32 v232, 0, v232
	v_max_f32_e32 v233, 0, v233
	v_max_f32_e32 v234, 0, v234
	v_max_f32_e32 v235, 0, v235
	v_max_f32_e32 v236, 0, v236
	v_max_f32_e32 v237, 0, v237
	s_waitcnt lgkmcnt(3)
	v_mfma_f32_32x32x16_f16 v[2:17], v[50:53], v[174:177], v[2:17]
	v_fmac_f32_e32 v108, v239, v182
	v_fmac_f32_e32 v109, v239, v183
	v_fmac_f32_e32 v110, v239, v184
	v_fmac_f32_e32 v111, v239, v185
	v_fmac_f32_e32 v104, v239, v186
	v_fmac_f32_e32 v105, v239, v187
	v_fmac_f32_e32 v106, v239, v188
	v_fmac_f32_e32 v107, v239, v189
	v_mfma_f32_32x32x16_f16 v[18:33], v[58:61], v[174:177], v[18:33]
	ds_read_b128 v[174:177], v69 offset:448
	v_fmac_f32_e32 v100, v239, v190
	v_fmac_f32_e32 v101, v239, v191
	v_fmac_f32_e32 v102, v239, v192
	v_fmac_f32_e32 v103, v239, v193
	v_fmac_f32_e32 v98, v239, v194
	v_fmac_f32_e32 v99, v239, v195
	v_fmac_f32_e32 v84, v239, v196
	v_fmac_f32_e32 v85, v239, v197
	s_waitcnt lgkmcnt(3)
	v_mfma_f32_32x32x16_f16 v[2:17], v[54:57], v[178:181], v[2:17]
	v_fmac_f32_e32 v94, v239, v222
	v_fmac_f32_e32 v95, v239, v223
	v_fmac_f32_e32 v96, v239, v224
	v_fmac_f32_e32 v97, v239, v225
	v_fmac_f32_e32 v90, v239, v226
	v_fmac_f32_e32 v91, v239, v227
	v_fmac_f32_e32 v92, v239, v228
	v_fmac_f32_e32 v93, v239, v229
	v_mfma_f32_32x32x16_f16 v[18:33], v[62:65], v[178:181], v[18:33]
	ds_read_b128 v[178:181], v69 offset:480
	v_fmac_f32_e32 v86, v239, v230
	v_fmac_f32_e32 v87, v239, v231
	v_fmac_f32_e32 v88, v239, v232
	v_fmac_f32_e32 v89, v239, v233
	v_fmac_f32_e32 v82, v239, v234
	v_fmac_f32_e32 v83, v239, v235
	v_fmac_f32_e32 v78, v239, v236
	v_fmac_f32_e32 v79, v239, v237
	s_waitcnt lgkmcnt(3)
	v_mfma_f32_32x32x16_f16 v[182:197], v[34:37], v[166:169], 0
	s_nop 1
	v_max_f32_e32 v2, 0, v2
	v_max_f32_e32 v3, 0, v3
	v_max_f32_e32 v4, 0, v4
	v_max_f32_e32 v5, 0, v5
	v_max_f32_e32 v6, 0, v6
	v_max_f32_e32 v7, 0, v7
	v_max_f32_e32 v8, 0, v8
	v_max_f32_e32 v9, 0, v9
	v_mfma_f32_32x32x16_f16 v[222:237], v[42:45], v[166:169], 0
	ds_read_b128 v[166:169], v69 offset:512
	v_max_f32_e32 v10, 0, v10
	v_max_f32_e32 v11, 0, v11
	v_max_f32_e32 v12, 0, v12
	v_max_f32_e32 v13, 0, v13
	v_max_f32_e32 v14, 0, v14
	v_max_f32_e32 v15, 0, v15
	v_max_f32_e32 v16, 0, v16
	v_max_f32_e32 v17, 0, v17
	s_waitcnt lgkmcnt(3)
	v_mfma_f32_32x32x16_f16 v[182:197], v[38:41], v[170:173], v[182:197]
	v_max_f32_e32 v18, 0, v18
	v_max_f32_e32 v19, 0, v19
	v_max_f32_e32 v20, 0, v20
	v_max_f32_e32 v21, 0, v21
	v_max_f32_e32 v22, 0, v22
	v_max_f32_e32 v23, 0, v23
	v_max_f32_e32 v24, 0, v24
	v_max_f32_e32 v25, 0, v25
	v_mfma_f32_32x32x16_f16 v[222:237], v[46:49], v[170:173], v[222:237]
	ds_read_b128 v[170:173], v69 offset:544
	v_max_f32_e32 v26, 0, v26
	v_max_f32_e32 v27, 0, v27
	v_max_f32_e32 v28, 0, v28
	v_max_f32_e32 v29, 0, v29
	v_max_f32_e32 v30, 0, v30
	v_max_f32_e32 v31, 0, v31
	v_max_f32_e32 v32, 0, v32
	v_max_f32_e32 v33, 0, v33
	s_waitcnt lgkmcnt(3)
	v_mfma_f32_32x32x16_f16 v[182:197], v[50:53], v[174:177], v[182:197]
	v_fmac_f32_e32 v108, v240, v2
	v_fmac_f32_e32 v109, v240, v3
	v_fmac_f32_e32 v110, v240, v4
	v_fmac_f32_e32 v111, v240, v5
	v_fmac_f32_e32 v104, v240, v6
	v_fmac_f32_e32 v105, v240, v7
	v_fmac_f32_e32 v106, v240, v8
	v_fmac_f32_e32 v107, v240, v9
	v_mfma_f32_32x32x16_f16 v[222:237], v[58:61], v[174:177], v[222:237]
	ds_read_b128 v[174:177], v69 offset:576
	v_fmac_f32_e32 v100, v240, v10
	v_fmac_f32_e32 v101, v240, v11
	v_fmac_f32_e32 v102, v240, v12
	v_fmac_f32_e32 v103, v240, v13
	v_fmac_f32_e32 v98, v240, v14
	v_fmac_f32_e32 v99, v240, v15
	v_fmac_f32_e32 v84, v240, v16
	v_fmac_f32_e32 v85, v240, v17
	s_waitcnt lgkmcnt(3)
	v_mfma_f32_32x32x16_f16 v[182:197], v[54:57], v[178:181], v[182:197]
	v_fmac_f32_e32 v94, v240, v18
	v_fmac_f32_e32 v95, v240, v19
	v_fmac_f32_e32 v96, v240, v20
	v_fmac_f32_e32 v97, v240, v21
	v_fmac_f32_e32 v90, v240, v22
	v_fmac_f32_e32 v91, v240, v23
	v_fmac_f32_e32 v92, v240, v24
	v_fmac_f32_e32 v93, v240, v25
	v_mfma_f32_32x32x16_f16 v[222:237], v[62:65], v[178:181], v[222:237]
	ds_read_b128 v[178:181], v69 offset:608
	v_fmac_f32_e32 v86, v240, v26
	v_fmac_f32_e32 v87, v240, v27
	v_fmac_f32_e32 v88, v240, v28
	v_fmac_f32_e32 v89, v240, v29
	v_fmac_f32_e32 v82, v240, v30
	v_fmac_f32_e32 v83, v240, v31
	v_fmac_f32_e32 v78, v240, v32
	v_fmac_f32_e32 v79, v240, v33
	s_waitcnt lgkmcnt(3)
	v_mfma_f32_32x32x16_f16 v[2:17], v[34:37], v[166:169], 0
	s_nop 1
	v_max_f32_e32 v182, 0, v182
	v_max_f32_e32 v183, 0, v183
	v_max_f32_e32 v184, 0, v184
	v_max_f32_e32 v185, 0, v185
	v_max_f32_e32 v186, 0, v186
	v_max_f32_e32 v187, 0, v187
	v_max_f32_e32 v188, 0, v188
	v_max_f32_e32 v189, 0, v189
	v_mfma_f32_32x32x16_f16 v[18:33], v[42:45], v[166:169], 0
	ds_read_b128 v[166:169], v69 offset:640
	v_max_f32_e32 v190, 0, v190
	v_max_f32_e32 v191, 0, v191
	v_max_f32_e32 v192, 0, v192
	v_max_f32_e32 v193, 0, v193
	v_max_f32_e32 v194, 0, v194
	v_max_f32_e32 v195, 0, v195
	v_max_f32_e32 v196, 0, v196
	v_max_f32_e32 v197, 0, v197
	s_waitcnt lgkmcnt(3)
	v_mfma_f32_32x32x16_f16 v[2:17], v[38:41], v[170:173], v[2:17]
	v_max_f32_e32 v222, 0, v222
	v_max_f32_e32 v223, 0, v223
	v_max_f32_e32 v224, 0, v224
	v_max_f32_e32 v225, 0, v225
	v_max_f32_e32 v226, 0, v226
	v_max_f32_e32 v227, 0, v227
	v_max_f32_e32 v228, 0, v228
	v_max_f32_e32 v229, 0, v229
	v_mfma_f32_32x32x16_f16 v[18:33], v[46:49], v[170:173], v[18:33]
	ds_read_b128 v[170:173], v69 offset:672
	v_max_f32_e32 v230, 0, v230
	v_max_f32_e32 v231, 0, v231
	v_max_f32_e32 v232, 0, v232
	v_max_f32_e32 v233, 0, v233
	v_max_f32_e32 v234, 0, v234
	v_max_f32_e32 v235, 0, v235
	v_max_f32_e32 v236, 0, v236
	v_max_f32_e32 v237, 0, v237
	s_waitcnt lgkmcnt(3)
	v_mfma_f32_32x32x16_f16 v[2:17], v[50:53], v[174:177], v[2:17]
	v_fmac_f32_e32 v108, v241, v182
	v_fmac_f32_e32 v109, v241, v183
	v_fmac_f32_e32 v110, v241, v184
	v_fmac_f32_e32 v111, v241, v185
	v_fmac_f32_e32 v104, v241, v186
	v_fmac_f32_e32 v105, v241, v187
	v_fmac_f32_e32 v106, v241, v188
	v_fmac_f32_e32 v107, v241, v189
	v_mfma_f32_32x32x16_f16 v[18:33], v[58:61], v[174:177], v[18:33]
	ds_read_b128 v[174:177], v69 offset:704
	v_fmac_f32_e32 v100, v241, v190
	v_fmac_f32_e32 v101, v241, v191
	v_fmac_f32_e32 v102, v241, v192
	v_fmac_f32_e32 v103, v241, v193
	v_fmac_f32_e32 v98, v241, v194
	v_fmac_f32_e32 v99, v241, v195
	v_fmac_f32_e32 v84, v241, v196
	v_fmac_f32_e32 v85, v241, v197
	s_waitcnt lgkmcnt(3)
	v_mfma_f32_32x32x16_f16 v[2:17], v[54:57], v[178:181], v[2:17]
	v_fmac_f32_e32 v94, v241, v222
	v_fmac_f32_e32 v95, v241, v223
	v_fmac_f32_e32 v96, v241, v224
	v_fmac_f32_e32 v97, v241, v225
	v_fmac_f32_e32 v90, v241, v226
	v_fmac_f32_e32 v91, v241, v227
	v_fmac_f32_e32 v92, v241, v228
	v_fmac_f32_e32 v93, v241, v229
	v_mfma_f32_32x32x16_f16 v[18:33], v[62:65], v[178:181], v[18:33]
	ds_read_b128 v[178:181], v69 offset:736
	v_fmac_f32_e32 v86, v241, v230
	v_fmac_f32_e32 v87, v241, v231
	v_fmac_f32_e32 v88, v241, v232
	v_fmac_f32_e32 v89, v241, v233
	v_fmac_f32_e32 v82, v241, v234
	v_fmac_f32_e32 v83, v241, v235
	v_fmac_f32_e32 v78, v241, v236
	v_fmac_f32_e32 v79, v241, v237
	s_waitcnt lgkmcnt(3)
	v_mfma_f32_32x32x16_f16 v[182:197], v[34:37], v[166:169], 0
	s_nop 1
	v_max_f32_e32 v2, 0, v2
	v_max_f32_e32 v3, 0, v3
	v_max_f32_e32 v4, 0, v4
	v_max_f32_e32 v5, 0, v5
	v_max_f32_e32 v6, 0, v6
	v_max_f32_e32 v7, 0, v7
	v_max_f32_e32 v8, 0, v8
	v_max_f32_e32 v9, 0, v9
	v_mfma_f32_32x32x16_f16 v[222:237], v[42:45], v[166:169], 0
	ds_read_b128 v[166:169], v69 offset:768
	v_max_f32_e32 v10, 0, v10
	v_max_f32_e32 v11, 0, v11
	v_max_f32_e32 v12, 0, v12
	v_max_f32_e32 v13, 0, v13
	v_max_f32_e32 v14, 0, v14
	v_max_f32_e32 v15, 0, v15
	v_max_f32_e32 v16, 0, v16
	v_max_f32_e32 v17, 0, v17
	s_waitcnt lgkmcnt(3)
	v_mfma_f32_32x32x16_f16 v[182:197], v[38:41], v[170:173], v[182:197]
	v_max_f32_e32 v18, 0, v18
	v_max_f32_e32 v19, 0, v19
	v_max_f32_e32 v20, 0, v20
	v_max_f32_e32 v21, 0, v21
	v_max_f32_e32 v22, 0, v22
	v_max_f32_e32 v23, 0, v23
	v_max_f32_e32 v24, 0, v24
	v_max_f32_e32 v25, 0, v25
	v_mfma_f32_32x32x16_f16 v[222:237], v[46:49], v[170:173], v[222:237]
	ds_read_b128 v[170:173], v69 offset:800
	v_max_f32_e32 v26, 0, v26
	v_max_f32_e32 v27, 0, v27
	v_max_f32_e32 v28, 0, v28
	v_max_f32_e32 v29, 0, v29
	v_max_f32_e32 v30, 0, v30
	v_max_f32_e32 v31, 0, v31
	v_max_f32_e32 v32, 0, v32
	v_max_f32_e32 v33, 0, v33
	s_waitcnt lgkmcnt(3)
	v_mfma_f32_32x32x16_f16 v[182:197], v[50:53], v[174:177], v[182:197]
	v_fmac_f32_e32 v108, v242, v2
	v_fmac_f32_e32 v109, v242, v3
	v_fmac_f32_e32 v110, v242, v4
	v_fmac_f32_e32 v111, v242, v5
	v_fmac_f32_e32 v104, v242, v6
	v_fmac_f32_e32 v105, v242, v7
	v_fmac_f32_e32 v106, v242, v8
	v_fmac_f32_e32 v107, v242, v9
	v_mfma_f32_32x32x16_f16 v[222:237], v[58:61], v[174:177], v[222:237]
	ds_read_b128 v[174:177], v69 offset:832
	v_fmac_f32_e32 v100, v242, v10
	v_fmac_f32_e32 v101, v242, v11
	v_fmac_f32_e32 v102, v242, v12
	v_fmac_f32_e32 v103, v242, v13
	v_fmac_f32_e32 v98, v242, v14
	v_fmac_f32_e32 v99, v242, v15
	v_fmac_f32_e32 v84, v242, v16
	v_fmac_f32_e32 v85, v242, v17
	s_waitcnt lgkmcnt(3)
	v_mfma_f32_32x32x16_f16 v[182:197], v[54:57], v[178:181], v[182:197]
	v_fmac_f32_e32 v94, v242, v18
	v_fmac_f32_e32 v95, v242, v19
	v_fmac_f32_e32 v96, v242, v20
	v_fmac_f32_e32 v97, v242, v21
	v_fmac_f32_e32 v90, v242, v22
	v_fmac_f32_e32 v91, v242, v23
	v_fmac_f32_e32 v92, v242, v24
	v_fmac_f32_e32 v93, v242, v25
	v_mfma_f32_32x32x16_f16 v[222:237], v[62:65], v[178:181], v[222:237]
	ds_read_b128 v[178:181], v69 offset:864
	v_fmac_f32_e32 v86, v242, v26
	v_fmac_f32_e32 v87, v242, v27
	v_fmac_f32_e32 v88, v242, v28
	v_fmac_f32_e32 v89, v242, v29
	v_fmac_f32_e32 v82, v242, v30
	v_fmac_f32_e32 v83, v242, v31
	v_fmac_f32_e32 v78, v242, v32
	v_fmac_f32_e32 v79, v242, v33
	s_waitcnt lgkmcnt(3)
	v_mfma_f32_32x32x16_f16 v[2:17], v[34:37], v[166:169], 0
	s_nop 1
	v_max_f32_e32 v182, 0, v182
	v_max_f32_e32 v183, 0, v183
	v_max_f32_e32 v184, 0, v184
	v_max_f32_e32 v185, 0, v185
	v_max_f32_e32 v186, 0, v186
	v_max_f32_e32 v187, 0, v187
	v_max_f32_e32 v188, 0, v188
	v_max_f32_e32 v189, 0, v189
	v_mfma_f32_32x32x16_f16 v[18:33], v[42:45], v[166:169], 0
	ds_read_b128 v[166:169], v69 offset:896
	v_max_f32_e32 v190, 0, v190
	v_max_f32_e32 v191, 0, v191
	v_max_f32_e32 v192, 0, v192
	v_max_f32_e32 v193, 0, v193
	v_max_f32_e32 v194, 0, v194
	v_max_f32_e32 v195, 0, v195
	v_max_f32_e32 v196, 0, v196
	v_max_f32_e32 v197, 0, v197
	s_waitcnt lgkmcnt(3)
	v_mfma_f32_32x32x16_f16 v[2:17], v[38:41], v[170:173], v[2:17]
	v_max_f32_e32 v222, 0, v222
	v_max_f32_e32 v223, 0, v223
	v_max_f32_e32 v224, 0, v224
	v_max_f32_e32 v225, 0, v225
	v_max_f32_e32 v226, 0, v226
	v_max_f32_e32 v227, 0, v227
	v_max_f32_e32 v228, 0, v228
	v_max_f32_e32 v229, 0, v229
	v_mfma_f32_32x32x16_f16 v[18:33], v[46:49], v[170:173], v[18:33]
	ds_read_b128 v[170:173], v69 offset:928
	v_max_f32_e32 v230, 0, v230
	v_max_f32_e32 v231, 0, v231
	v_max_f32_e32 v232, 0, v232
	v_max_f32_e32 v233, 0, v233
	v_max_f32_e32 v234, 0, v234
	v_max_f32_e32 v235, 0, v235
	v_max_f32_e32 v236, 0, v236
	v_max_f32_e32 v237, 0, v237
	s_waitcnt lgkmcnt(3)
	v_mfma_f32_32x32x16_f16 v[2:17], v[50:53], v[174:177], v[2:17]
	v_fmac_f32_e32 v108, v243, v182
	v_fmac_f32_e32 v109, v243, v183
	v_fmac_f32_e32 v110, v243, v184
	v_fmac_f32_e32 v111, v243, v185
	v_fmac_f32_e32 v104, v243, v186
	v_fmac_f32_e32 v105, v243, v187
	v_fmac_f32_e32 v106, v243, v188
	v_fmac_f32_e32 v107, v243, v189
	v_mfma_f32_32x32x16_f16 v[18:33], v[58:61], v[174:177], v[18:33]
	ds_read_b128 v[174:177], v69 offset:960
	v_fmac_f32_e32 v100, v243, v190
	v_fmac_f32_e32 v101, v243, v191
	v_fmac_f32_e32 v102, v243, v192
	v_fmac_f32_e32 v103, v243, v193
	v_fmac_f32_e32 v98, v243, v194
	v_fmac_f32_e32 v99, v243, v195
	v_fmac_f32_e32 v84, v243, v196
	v_fmac_f32_e32 v85, v243, v197
	s_waitcnt lgkmcnt(3)
	v_mfma_f32_32x32x16_f16 v[2:17], v[54:57], v[178:181], v[2:17]
	v_fmac_f32_e32 v94, v243, v222
	v_fmac_f32_e32 v95, v243, v223
	v_fmac_f32_e32 v96, v243, v224
	v_fmac_f32_e32 v97, v243, v225
	v_fmac_f32_e32 v90, v243, v226
	v_fmac_f32_e32 v91, v243, v227
	v_fmac_f32_e32 v92, v243, v228
	v_fmac_f32_e32 v93, v243, v229
	v_mfma_f32_32x32x16_f16 v[18:33], v[62:65], v[178:181], v[18:33]
	ds_read_b128 v[178:181], v69 offset:992
	v_fmac_f32_e32 v86, v243, v230
	v_fmac_f32_e32 v87, v243, v231
	v_fmac_f32_e32 v88, v243, v232
	v_fmac_f32_e32 v89, v243, v233
	v_fmac_f32_e32 v82, v243, v234
	v_fmac_f32_e32 v83, v243, v235
	v_fmac_f32_e32 v78, v243, v236
	v_fmac_f32_e32 v79, v243, v237
	s_waitcnt lgkmcnt(3)
	v_mfma_f32_32x32x16_f16 v[182:197], v[34:37], v[166:169], 0
	s_nop 1
	v_max_f32_e32 v2, 0, v2
	v_max_f32_e32 v3, 0, v3
	v_max_f32_e32 v4, 0, v4
	v_max_f32_e32 v5, 0, v5
	v_max_f32_e32 v6, 0, v6
	v_max_f32_e32 v7, 0, v7
	v_max_f32_e32 v8, 0, v8
	v_max_f32_e32 v9, 0, v9
	v_mfma_f32_32x32x16_f16 v[222:237], v[42:45], v[166:169], 0
	ds_read_b128 v[166:169], v69 offset:1024
	v_max_f32_e32 v10, 0, v10
	v_max_f32_e32 v11, 0, v11
	v_max_f32_e32 v12, 0, v12
	v_max_f32_e32 v13, 0, v13
	v_max_f32_e32 v14, 0, v14
	v_max_f32_e32 v15, 0, v15
	v_max_f32_e32 v16, 0, v16
	v_max_f32_e32 v17, 0, v17
	s_waitcnt lgkmcnt(3)
	v_mfma_f32_32x32x16_f16 v[182:197], v[38:41], v[170:173], v[182:197]
	v_max_f32_e32 v18, 0, v18
	v_max_f32_e32 v19, 0, v19
	v_max_f32_e32 v20, 0, v20
	v_max_f32_e32 v21, 0, v21
	v_max_f32_e32 v22, 0, v22
	v_max_f32_e32 v23, 0, v23
	v_max_f32_e32 v24, 0, v24
	v_max_f32_e32 v25, 0, v25
	v_mfma_f32_32x32x16_f16 v[222:237], v[46:49], v[170:173], v[222:237]
	ds_read_b128 v[170:173], v69 offset:1056
	v_max_f32_e32 v26, 0, v26
	v_max_f32_e32 v27, 0, v27
	v_max_f32_e32 v28, 0, v28
	v_max_f32_e32 v29, 0, v29
	v_max_f32_e32 v30, 0, v30
	v_max_f32_e32 v31, 0, v31
	v_max_f32_e32 v32, 0, v32
	v_max_f32_e32 v33, 0, v33
	s_waitcnt lgkmcnt(3)
	v_mfma_f32_32x32x16_f16 v[182:197], v[50:53], v[174:177], v[182:197]
	v_fmac_f32_e32 v108, v244, v2
	v_fmac_f32_e32 v109, v244, v3
	v_fmac_f32_e32 v110, v244, v4
	v_fmac_f32_e32 v111, v244, v5
	v_fmac_f32_e32 v104, v244, v6
	v_fmac_f32_e32 v105, v244, v7
	v_fmac_f32_e32 v106, v244, v8
	v_fmac_f32_e32 v107, v244, v9
	v_mfma_f32_32x32x16_f16 v[222:237], v[58:61], v[174:177], v[222:237]
	ds_read_b128 v[174:177], v69 offset:1088
	v_fmac_f32_e32 v100, v244, v10
	v_fmac_f32_e32 v101, v244, v11
	v_fmac_f32_e32 v102, v244, v12
	v_fmac_f32_e32 v103, v244, v13
	v_fmac_f32_e32 v98, v244, v14
	v_fmac_f32_e32 v99, v244, v15
	v_fmac_f32_e32 v84, v244, v16
	v_fmac_f32_e32 v85, v244, v17
	s_waitcnt lgkmcnt(3)
	v_mfma_f32_32x32x16_f16 v[182:197], v[54:57], v[178:181], v[182:197]
	v_fmac_f32_e32 v94, v244, v18
	v_fmac_f32_e32 v95, v244, v19
	v_fmac_f32_e32 v96, v244, v20
	v_fmac_f32_e32 v97, v244, v21
	v_fmac_f32_e32 v90, v244, v22
	v_fmac_f32_e32 v91, v244, v23
	v_fmac_f32_e32 v92, v244, v24
	v_fmac_f32_e32 v93, v244, v25
	v_mfma_f32_32x32x16_f16 v[222:237], v[62:65], v[178:181], v[222:237]
	ds_read_b128 v[178:181], v69 offset:1120
	v_fmac_f32_e32 v86, v244, v26
	v_fmac_f32_e32 v87, v244, v27
	v_fmac_f32_e32 v88, v244, v28
	v_fmac_f32_e32 v89, v244, v29
	v_fmac_f32_e32 v82, v244, v30
	v_fmac_f32_e32 v83, v244, v31
	v_fmac_f32_e32 v78, v244, v32
	v_fmac_f32_e32 v79, v244, v33
	s_waitcnt lgkmcnt(3)
	v_mfma_f32_32x32x16_f16 v[2:17], v[34:37], v[166:169], 0
	s_nop 1
	v_max_f32_e32 v182, 0, v182
	v_max_f32_e32 v183, 0, v183
	v_max_f32_e32 v184, 0, v184
	v_max_f32_e32 v185, 0, v185
	v_max_f32_e32 v186, 0, v186
	v_max_f32_e32 v187, 0, v187
	v_max_f32_e32 v188, 0, v188
	v_max_f32_e32 v189, 0, v189
	v_mfma_f32_32x32x16_f16 v[18:33], v[42:45], v[166:169], 0
	ds_read_b128 v[166:169], v69 offset:1152
	v_max_f32_e32 v190, 0, v190
	v_max_f32_e32 v191, 0, v191
	v_max_f32_e32 v192, 0, v192
	v_max_f32_e32 v193, 0, v193
	v_max_f32_e32 v194, 0, v194
	v_max_f32_e32 v195, 0, v195
	v_max_f32_e32 v196, 0, v196
	v_max_f32_e32 v197, 0, v197
	s_waitcnt lgkmcnt(3)
	v_mfma_f32_32x32x16_f16 v[2:17], v[38:41], v[170:173], v[2:17]
	v_max_f32_e32 v222, 0, v222
	v_max_f32_e32 v223, 0, v223
	v_max_f32_e32 v224, 0, v224
	v_max_f32_e32 v225, 0, v225
	v_max_f32_e32 v226, 0, v226
	v_max_f32_e32 v227, 0, v227
	v_max_f32_e32 v228, 0, v228
	v_max_f32_e32 v229, 0, v229
	v_mfma_f32_32x32x16_f16 v[18:33], v[46:49], v[170:173], v[18:33]
	ds_read_b128 v[170:173], v69 offset:1184
	v_max_f32_e32 v230, 0, v230
	v_max_f32_e32 v231, 0, v231
	v_max_f32_e32 v232, 0, v232
	v_max_f32_e32 v233, 0, v233
	v_max_f32_e32 v234, 0, v234
	v_max_f32_e32 v235, 0, v235
	v_max_f32_e32 v236, 0, v236
	v_max_f32_e32 v237, 0, v237
	s_waitcnt lgkmcnt(3)
	v_mfma_f32_32x32x16_f16 v[2:17], v[50:53], v[174:177], v[2:17]
	v_fmac_f32_e32 v108, v245, v182
	v_fmac_f32_e32 v109, v245, v183
	v_fmac_f32_e32 v110, v245, v184
	v_fmac_f32_e32 v111, v245, v185
	v_fmac_f32_e32 v104, v245, v186
	v_fmac_f32_e32 v105, v245, v187
	v_fmac_f32_e32 v106, v245, v188
	v_fmac_f32_e32 v107, v245, v189
	v_mfma_f32_32x32x16_f16 v[18:33], v[58:61], v[174:177], v[18:33]
	ds_read_b128 v[174:177], v69 offset:1216
	v_fmac_f32_e32 v100, v245, v190
	v_fmac_f32_e32 v101, v245, v191
	v_fmac_f32_e32 v102, v245, v192
	v_fmac_f32_e32 v103, v245, v193
	v_fmac_f32_e32 v98, v245, v194
	v_fmac_f32_e32 v99, v245, v195
	v_fmac_f32_e32 v84, v245, v196
	v_fmac_f32_e32 v85, v245, v197
	s_waitcnt lgkmcnt(3)
	v_mfma_f32_32x32x16_f16 v[2:17], v[54:57], v[178:181], v[2:17]
	v_fmac_f32_e32 v94, v245, v222
	v_fmac_f32_e32 v95, v245, v223
	v_fmac_f32_e32 v96, v245, v224
	v_fmac_f32_e32 v97, v245, v225
	v_fmac_f32_e32 v90, v245, v226
	v_fmac_f32_e32 v91, v245, v227
	v_fmac_f32_e32 v92, v245, v228
	v_fmac_f32_e32 v93, v245, v229
	v_mfma_f32_32x32x16_f16 v[18:33], v[62:65], v[178:181], v[18:33]
	ds_read_b128 v[178:181], v69 offset:1248
	v_fmac_f32_e32 v86, v245, v230
	v_fmac_f32_e32 v87, v245, v231
	v_fmac_f32_e32 v88, v245, v232
	v_fmac_f32_e32 v89, v245, v233
	v_fmac_f32_e32 v82, v245, v234
	v_fmac_f32_e32 v83, v245, v235
	v_fmac_f32_e32 v78, v245, v236
	v_fmac_f32_e32 v79, v245, v237
	s_waitcnt lgkmcnt(3)
	v_mfma_f32_32x32x16_f16 v[182:197], v[34:37], v[166:169], 0
	s_nop 1
	v_max_f32_e32 v2, 0, v2
	v_max_f32_e32 v3, 0, v3
	v_max_f32_e32 v4, 0, v4
	v_max_f32_e32 v5, 0, v5
	v_max_f32_e32 v6, 0, v6
	v_max_f32_e32 v7, 0, v7
	v_max_f32_e32 v8, 0, v8
	v_max_f32_e32 v9, 0, v9
	v_mfma_f32_32x32x16_f16 v[222:237], v[42:45], v[166:169], 0
	ds_read_b128 v[166:169], v69 offset:1280
	v_max_f32_e32 v10, 0, v10
	v_max_f32_e32 v11, 0, v11
	v_max_f32_e32 v12, 0, v12
	v_max_f32_e32 v13, 0, v13
	v_max_f32_e32 v14, 0, v14
	v_max_f32_e32 v15, 0, v15
	v_max_f32_e32 v16, 0, v16
	v_max_f32_e32 v17, 0, v17
	s_waitcnt lgkmcnt(3)
	v_mfma_f32_32x32x16_f16 v[182:197], v[38:41], v[170:173], v[182:197]
	v_max_f32_e32 v18, 0, v18
	v_max_f32_e32 v19, 0, v19
	v_max_f32_e32 v20, 0, v20
	v_max_f32_e32 v21, 0, v21
	v_max_f32_e32 v22, 0, v22
	v_max_f32_e32 v23, 0, v23
	v_max_f32_e32 v24, 0, v24
	v_max_f32_e32 v25, 0, v25
	v_mfma_f32_32x32x16_f16 v[222:237], v[46:49], v[170:173], v[222:237]
	ds_read_b128 v[170:173], v69 offset:1312
	v_max_f32_e32 v26, 0, v26
	v_max_f32_e32 v27, 0, v27
	v_max_f32_e32 v28, 0, v28
	v_max_f32_e32 v29, 0, v29
	v_max_f32_e32 v30, 0, v30
	v_max_f32_e32 v31, 0, v31
	v_max_f32_e32 v32, 0, v32
	v_max_f32_e32 v33, 0, v33
	s_waitcnt lgkmcnt(3)
	v_mfma_f32_32x32x16_f16 v[182:197], v[50:53], v[174:177], v[182:197]
	v_fmac_f32_e32 v108, v246, v2
	v_fmac_f32_e32 v109, v246, v3
	v_fmac_f32_e32 v110, v246, v4
	v_fmac_f32_e32 v111, v246, v5
	v_fmac_f32_e32 v104, v246, v6
	v_fmac_f32_e32 v105, v246, v7
	v_fmac_f32_e32 v106, v246, v8
	v_fmac_f32_e32 v107, v246, v9
	v_mfma_f32_32x32x16_f16 v[222:237], v[58:61], v[174:177], v[222:237]
	ds_read_b128 v[174:177], v69 offset:1344
	v_fmac_f32_e32 v100, v246, v10
	v_fmac_f32_e32 v101, v246, v11
	v_fmac_f32_e32 v102, v246, v12
	v_fmac_f32_e32 v103, v246, v13
	v_fmac_f32_e32 v98, v246, v14
	v_fmac_f32_e32 v99, v246, v15
	v_fmac_f32_e32 v84, v246, v16
	v_fmac_f32_e32 v85, v246, v17
	s_waitcnt lgkmcnt(3)
	v_mfma_f32_32x32x16_f16 v[182:197], v[54:57], v[178:181], v[182:197]
	v_fmac_f32_e32 v94, v246, v18
	v_fmac_f32_e32 v95, v246, v19
	v_fmac_f32_e32 v96, v246, v20
	v_fmac_f32_e32 v97, v246, v21
	v_fmac_f32_e32 v90, v246, v22
	v_fmac_f32_e32 v91, v246, v23
	v_fmac_f32_e32 v92, v246, v24
	v_fmac_f32_e32 v93, v246, v25
	v_mfma_f32_32x32x16_f16 v[222:237], v[62:65], v[178:181], v[222:237]
	ds_read_b128 v[178:181], v69 offset:1376
	v_fmac_f32_e32 v86, v246, v26
	v_fmac_f32_e32 v87, v246, v27
	v_fmac_f32_e32 v88, v246, v28
	v_fmac_f32_e32 v89, v246, v29
	v_fmac_f32_e32 v82, v246, v30
	v_fmac_f32_e32 v83, v246, v31
	v_fmac_f32_e32 v78, v246, v32
	v_fmac_f32_e32 v79, v246, v33
	s_waitcnt lgkmcnt(3)
	v_mfma_f32_32x32x16_f16 v[2:17], v[34:37], v[166:169], 0
	s_nop 1
	v_max_f32_e32 v182, 0, v182
	v_max_f32_e32 v183, 0, v183
	v_max_f32_e32 v184, 0, v184
	v_max_f32_e32 v185, 0, v185
	v_max_f32_e32 v186, 0, v186
	v_max_f32_e32 v187, 0, v187
	v_max_f32_e32 v188, 0, v188
	v_max_f32_e32 v189, 0, v189
	v_mfma_f32_32x32x16_f16 v[18:33], v[42:45], v[166:169], 0
	ds_read_b128 v[166:169], v69 offset:1408
	v_max_f32_e32 v190, 0, v190
	v_max_f32_e32 v191, 0, v191
	v_max_f32_e32 v192, 0, v192
	v_max_f32_e32 v193, 0, v193
	v_max_f32_e32 v194, 0, v194
	v_max_f32_e32 v195, 0, v195
	v_max_f32_e32 v196, 0, v196
	v_max_f32_e32 v197, 0, v197
	s_waitcnt lgkmcnt(3)
	v_mfma_f32_32x32x16_f16 v[2:17], v[38:41], v[170:173], v[2:17]
	v_max_f32_e32 v222, 0, v222
	v_max_f32_e32 v223, 0, v223
	v_max_f32_e32 v224, 0, v224
	v_max_f32_e32 v225, 0, v225
	v_max_f32_e32 v226, 0, v226
	v_max_f32_e32 v227, 0, v227
	v_max_f32_e32 v228, 0, v228
	v_max_f32_e32 v229, 0, v229
	v_mfma_f32_32x32x16_f16 v[18:33], v[46:49], v[170:173], v[18:33]
	ds_read_b128 v[170:173], v69 offset:1440
	v_max_f32_e32 v230, 0, v230
	v_max_f32_e32 v231, 0, v231
	v_max_f32_e32 v232, 0, v232
	v_max_f32_e32 v233, 0, v233
	v_max_f32_e32 v234, 0, v234
	v_max_f32_e32 v235, 0, v235
	v_max_f32_e32 v236, 0, v236
	v_max_f32_e32 v237, 0, v237
	s_waitcnt lgkmcnt(3)
	v_mfma_f32_32x32x16_f16 v[2:17], v[50:53], v[174:177], v[2:17]
	v_fmac_f32_e32 v108, v247, v182
	v_fmac_f32_e32 v109, v247, v183
	v_fmac_f32_e32 v110, v247, v184
	v_fmac_f32_e32 v111, v247, v185
	v_fmac_f32_e32 v104, v247, v186
	v_fmac_f32_e32 v105, v247, v187
	v_fmac_f32_e32 v106, v247, v188
	v_fmac_f32_e32 v107, v247, v189
	v_mfma_f32_32x32x16_f16 v[18:33], v[58:61], v[174:177], v[18:33]
	ds_read_b128 v[174:177], v69 offset:1472
	v_fmac_f32_e32 v100, v247, v190
	v_fmac_f32_e32 v101, v247, v191
	v_fmac_f32_e32 v102, v247, v192
	v_fmac_f32_e32 v103, v247, v193
	v_fmac_f32_e32 v98, v247, v194
	v_fmac_f32_e32 v99, v247, v195
	v_fmac_f32_e32 v84, v247, v196
	v_fmac_f32_e32 v85, v247, v197
	s_waitcnt lgkmcnt(3)
	v_mfma_f32_32x32x16_f16 v[2:17], v[54:57], v[178:181], v[2:17]
	v_fmac_f32_e32 v94, v247, v222
	v_fmac_f32_e32 v95, v247, v223
	v_fmac_f32_e32 v96, v247, v224
	v_fmac_f32_e32 v97, v247, v225
	v_fmac_f32_e32 v90, v247, v226
	v_fmac_f32_e32 v91, v247, v227
	v_fmac_f32_e32 v92, v247, v228
	v_fmac_f32_e32 v93, v247, v229
	v_mfma_f32_32x32x16_f16 v[18:33], v[62:65], v[178:181], v[18:33]
	ds_read_b128 v[178:181], v69 offset:1504
	v_fmac_f32_e32 v86, v247, v230
	v_fmac_f32_e32 v87, v247, v231
	v_fmac_f32_e32 v88, v247, v232
	v_fmac_f32_e32 v89, v247, v233
	v_fmac_f32_e32 v82, v247, v234
	v_fmac_f32_e32 v83, v247, v235
	v_fmac_f32_e32 v78, v247, v236
	v_fmac_f32_e32 v79, v247, v237
	s_waitcnt lgkmcnt(3)
	v_mfma_f32_32x32x16_f16 v[182:197], v[34:37], v[166:169], 0
	s_nop 1
	v_max_f32_e32 v2, 0, v2
	v_max_f32_e32 v3, 0, v3
	v_max_f32_e32 v4, 0, v4
	v_max_f32_e32 v5, 0, v5
	v_max_f32_e32 v6, 0, v6
	v_max_f32_e32 v7, 0, v7
	v_max_f32_e32 v8, 0, v8
	v_max_f32_e32 v9, 0, v9
	v_mfma_f32_32x32x16_f16 v[222:237], v[42:45], v[166:169], 0
	ds_read_b128 v[166:169], v69 offset:1536
	v_max_f32_e32 v10, 0, v10
	v_max_f32_e32 v11, 0, v11
	v_max_f32_e32 v12, 0, v12
	v_max_f32_e32 v13, 0, v13
	v_max_f32_e32 v14, 0, v14
	v_max_f32_e32 v15, 0, v15
	v_max_f32_e32 v16, 0, v16
	v_max_f32_e32 v17, 0, v17
	s_waitcnt lgkmcnt(3)
	v_mfma_f32_32x32x16_f16 v[182:197], v[38:41], v[170:173], v[182:197]
	v_max_f32_e32 v18, 0, v18
	v_max_f32_e32 v19, 0, v19
	v_max_f32_e32 v20, 0, v20
	v_max_f32_e32 v21, 0, v21
	v_max_f32_e32 v22, 0, v22
	v_max_f32_e32 v23, 0, v23
	v_max_f32_e32 v24, 0, v24
	v_max_f32_e32 v25, 0, v25
	v_mfma_f32_32x32x16_f16 v[222:237], v[46:49], v[170:173], v[222:237]
	ds_read_b128 v[170:173], v69 offset:1568
	v_max_f32_e32 v26, 0, v26
	v_max_f32_e32 v27, 0, v27
	v_max_f32_e32 v28, 0, v28
	v_max_f32_e32 v29, 0, v29
	v_max_f32_e32 v30, 0, v30
	v_max_f32_e32 v31, 0, v31
	v_max_f32_e32 v32, 0, v32
	v_max_f32_e32 v33, 0, v33
	s_waitcnt lgkmcnt(3)
	v_mfma_f32_32x32x16_f16 v[182:197], v[50:53], v[174:177], v[182:197]
	v_fmac_f32_e32 v108, v248, v2
	v_fmac_f32_e32 v109, v248, v3
	v_fmac_f32_e32 v110, v248, v4
	v_fmac_f32_e32 v111, v248, v5
	v_fmac_f32_e32 v104, v248, v6
	v_fmac_f32_e32 v105, v248, v7
	v_fmac_f32_e32 v106, v248, v8
	v_fmac_f32_e32 v107, v248, v9
	v_mfma_f32_32x32x16_f16 v[222:237], v[58:61], v[174:177], v[222:237]
	ds_read_b128 v[174:177], v69 offset:1600
	v_fmac_f32_e32 v100, v248, v10
	v_fmac_f32_e32 v101, v248, v11
	v_fmac_f32_e32 v102, v248, v12
	v_fmac_f32_e32 v103, v248, v13
	v_fmac_f32_e32 v98, v248, v14
	v_fmac_f32_e32 v99, v248, v15
	v_fmac_f32_e32 v84, v248, v16
	v_fmac_f32_e32 v85, v248, v17
	s_waitcnt lgkmcnt(3)
	v_mfma_f32_32x32x16_f16 v[182:197], v[54:57], v[178:181], v[182:197]
	v_fmac_f32_e32 v94, v248, v18
	v_fmac_f32_e32 v95, v248, v19
	v_fmac_f32_e32 v96, v248, v20
	v_fmac_f32_e32 v97, v248, v21
	v_fmac_f32_e32 v90, v248, v22
	v_fmac_f32_e32 v91, v248, v23
	v_fmac_f32_e32 v92, v248, v24
	v_fmac_f32_e32 v93, v248, v25
	v_mfma_f32_32x32x16_f16 v[222:237], v[62:65], v[178:181], v[222:237]
	ds_read_b128 v[178:181], v69 offset:1632
	v_fmac_f32_e32 v86, v248, v26
	v_fmac_f32_e32 v87, v248, v27
	v_fmac_f32_e32 v88, v248, v28
	v_fmac_f32_e32 v89, v248, v29
	v_fmac_f32_e32 v82, v248, v30
	v_fmac_f32_e32 v83, v248, v31
	v_fmac_f32_e32 v78, v248, v32
	v_fmac_f32_e32 v79, v248, v33
	s_waitcnt lgkmcnt(3)
	v_mfma_f32_32x32x16_f16 v[2:17], v[34:37], v[166:169], 0
	s_nop 1
	v_max_f32_e32 v182, 0, v182
	v_max_f32_e32 v183, 0, v183
	v_max_f32_e32 v184, 0, v184
	v_max_f32_e32 v185, 0, v185
	v_max_f32_e32 v186, 0, v186
	v_max_f32_e32 v187, 0, v187
	v_max_f32_e32 v188, 0, v188
	v_max_f32_e32 v189, 0, v189
	v_mfma_f32_32x32x16_f16 v[18:33], v[42:45], v[166:169], 0
	ds_read_b128 v[166:169], v69 offset:1664
	v_max_f32_e32 v190, 0, v190
	v_max_f32_e32 v191, 0, v191
	v_max_f32_e32 v192, 0, v192
	v_max_f32_e32 v193, 0, v193
	v_max_f32_e32 v194, 0, v194
	v_max_f32_e32 v195, 0, v195
	v_max_f32_e32 v196, 0, v196
	v_max_f32_e32 v197, 0, v197
	s_waitcnt lgkmcnt(3)
	v_mfma_f32_32x32x16_f16 v[2:17], v[38:41], v[170:173], v[2:17]
	v_max_f32_e32 v222, 0, v222
	v_max_f32_e32 v223, 0, v223
	v_max_f32_e32 v224, 0, v224
	v_max_f32_e32 v225, 0, v225
	v_max_f32_e32 v226, 0, v226
	v_max_f32_e32 v227, 0, v227
	v_max_f32_e32 v228, 0, v228
	v_max_f32_e32 v229, 0, v229
	v_mfma_f32_32x32x16_f16 v[18:33], v[46:49], v[170:173], v[18:33]
	ds_read_b128 v[170:173], v69 offset:1696
	v_max_f32_e32 v230, 0, v230
	v_max_f32_e32 v231, 0, v231
	v_max_f32_e32 v232, 0, v232
	v_max_f32_e32 v233, 0, v233
	v_max_f32_e32 v234, 0, v234
	v_max_f32_e32 v235, 0, v235
	v_max_f32_e32 v236, 0, v236
	v_max_f32_e32 v237, 0, v237
	s_waitcnt lgkmcnt(3)
	v_mfma_f32_32x32x16_f16 v[2:17], v[50:53], v[174:177], v[2:17]
	v_fmac_f32_e32 v108, v249, v182
	v_fmac_f32_e32 v109, v249, v183
	v_fmac_f32_e32 v110, v249, v184
	v_fmac_f32_e32 v111, v249, v185
	v_fmac_f32_e32 v104, v249, v186
	v_fmac_f32_e32 v105, v249, v187
	v_fmac_f32_e32 v106, v249, v188
	v_fmac_f32_e32 v107, v249, v189
	v_mfma_f32_32x32x16_f16 v[18:33], v[58:61], v[174:177], v[18:33]
	ds_read_b128 v[174:177], v69 offset:1728
	v_fmac_f32_e32 v100, v249, v190
	v_fmac_f32_e32 v101, v249, v191
	v_fmac_f32_e32 v102, v249, v192
	v_fmac_f32_e32 v103, v249, v193
	v_fmac_f32_e32 v98, v249, v194
	v_fmac_f32_e32 v99, v249, v195
	v_fmac_f32_e32 v84, v249, v196
	v_fmac_f32_e32 v85, v249, v197
	s_waitcnt lgkmcnt(3)
	v_mfma_f32_32x32x16_f16 v[2:17], v[54:57], v[178:181], v[2:17]
	v_fmac_f32_e32 v94, v249, v222
	v_fmac_f32_e32 v95, v249, v223
	v_fmac_f32_e32 v96, v249, v224
	v_fmac_f32_e32 v97, v249, v225
	v_fmac_f32_e32 v90, v249, v226
	v_fmac_f32_e32 v91, v249, v227
	v_fmac_f32_e32 v92, v249, v228
	v_fmac_f32_e32 v93, v249, v229
	v_mfma_f32_32x32x16_f16 v[18:33], v[62:65], v[178:181], v[18:33]
	ds_read_b128 v[178:181], v69 offset:1760
	v_fmac_f32_e32 v86, v249, v230
	v_fmac_f32_e32 v87, v249, v231
	v_fmac_f32_e32 v88, v249, v232
	v_fmac_f32_e32 v89, v249, v233
	v_fmac_f32_e32 v82, v249, v234
	v_fmac_f32_e32 v83, v249, v235
	v_fmac_f32_e32 v78, v249, v236
	v_fmac_f32_e32 v79, v249, v237
	s_waitcnt lgkmcnt(3)
	v_mfma_f32_32x32x16_f16 v[182:197], v[34:37], v[166:169], 0
	s_nop 1
	v_max_f32_e32 v2, 0, v2
	v_max_f32_e32 v3, 0, v3
	v_max_f32_e32 v4, 0, v4
	v_max_f32_e32 v5, 0, v5
	v_max_f32_e32 v6, 0, v6
	v_max_f32_e32 v7, 0, v7
	v_max_f32_e32 v8, 0, v8
	v_max_f32_e32 v9, 0, v9
	v_mfma_f32_32x32x16_f16 v[222:237], v[42:45], v[166:169], 0
	ds_read_b128 v[166:169], v69 offset:1792
	v_max_f32_e32 v10, 0, v10
	v_max_f32_e32 v11, 0, v11
	v_max_f32_e32 v12, 0, v12
	v_max_f32_e32 v13, 0, v13
	v_max_f32_e32 v14, 0, v14
	v_max_f32_e32 v15, 0, v15
	v_max_f32_e32 v16, 0, v16
	v_max_f32_e32 v17, 0, v17
	s_waitcnt lgkmcnt(3)
	v_mfma_f32_32x32x16_f16 v[182:197], v[38:41], v[170:173], v[182:197]
	v_max_f32_e32 v18, 0, v18
	v_max_f32_e32 v19, 0, v19
	v_max_f32_e32 v20, 0, v20
	v_max_f32_e32 v21, 0, v21
	v_max_f32_e32 v22, 0, v22
	v_max_f32_e32 v23, 0, v23
	v_max_f32_e32 v24, 0, v24
	v_max_f32_e32 v25, 0, v25
	v_mfma_f32_32x32x16_f16 v[222:237], v[46:49], v[170:173], v[222:237]
	ds_read_b128 v[170:173], v69 offset:1824
	v_max_f32_e32 v26, 0, v26
	v_max_f32_e32 v27, 0, v27
	v_max_f32_e32 v28, 0, v28
	v_max_f32_e32 v29, 0, v29
	v_max_f32_e32 v30, 0, v30
	v_max_f32_e32 v31, 0, v31
	v_max_f32_e32 v32, 0, v32
	v_max_f32_e32 v33, 0, v33
	s_waitcnt lgkmcnt(3)
	v_mfma_f32_32x32x16_f16 v[182:197], v[50:53], v[174:177], v[182:197]
	v_fmac_f32_e32 v108, v250, v2
	v_fmac_f32_e32 v109, v250, v3
	v_fmac_f32_e32 v110, v250, v4
	v_fmac_f32_e32 v111, v250, v5
	v_fmac_f32_e32 v104, v250, v6
	v_fmac_f32_e32 v105, v250, v7
	v_fmac_f32_e32 v106, v250, v8
	v_fmac_f32_e32 v107, v250, v9
	v_mfma_f32_32x32x16_f16 v[222:237], v[58:61], v[174:177], v[222:237]
	ds_read_b128 v[174:177], v69 offset:1856
	v_fmac_f32_e32 v100, v250, v10
	v_fmac_f32_e32 v101, v250, v11
	v_fmac_f32_e32 v102, v250, v12
	v_fmac_f32_e32 v103, v250, v13
	v_fmac_f32_e32 v98, v250, v14
	v_fmac_f32_e32 v99, v250, v15
	v_fmac_f32_e32 v84, v250, v16
	v_fmac_f32_e32 v85, v250, v17
	s_waitcnt lgkmcnt(3)
	v_mfma_f32_32x32x16_f16 v[182:197], v[54:57], v[178:181], v[182:197]
	v_fmac_f32_e32 v94, v250, v18
	v_fmac_f32_e32 v95, v250, v19
	v_fmac_f32_e32 v96, v250, v20
	v_fmac_f32_e32 v97, v250, v21
	v_fmac_f32_e32 v90, v250, v22
	v_fmac_f32_e32 v91, v250, v23
	v_fmac_f32_e32 v92, v250, v24
	v_fmac_f32_e32 v93, v250, v25
	v_mfma_f32_32x32x16_f16 v[222:237], v[62:65], v[178:181], v[222:237]
	ds_read_b128 v[178:181], v69 offset:1888
	v_fmac_f32_e32 v86, v250, v26
	v_fmac_f32_e32 v87, v250, v27
	v_fmac_f32_e32 v88, v250, v28
	v_fmac_f32_e32 v89, v250, v29
	v_fmac_f32_e32 v82, v250, v30
	v_fmac_f32_e32 v83, v250, v31
	v_fmac_f32_e32 v78, v250, v32
	v_fmac_f32_e32 v79, v250, v33
	s_waitcnt lgkmcnt(3)
	v_mfma_f32_32x32x16_f16 v[2:17], v[34:37], v[166:169], 0
	s_nop 1
	v_max_f32_e32 v182, 0, v182
	v_max_f32_e32 v183, 0, v183
	v_max_f32_e32 v184, 0, v184
	v_max_f32_e32 v185, 0, v185
	v_max_f32_e32 v186, 0, v186
	v_max_f32_e32 v187, 0, v187
	v_max_f32_e32 v188, 0, v188
	v_max_f32_e32 v189, 0, v189
	v_mfma_f32_32x32x16_f16 v[18:33], v[42:45], v[166:169], 0
	ds_read_b128 v[166:169], v69 offset:1920
	v_max_f32_e32 v190, 0, v190
	v_max_f32_e32 v191, 0, v191
	v_max_f32_e32 v192, 0, v192
	v_max_f32_e32 v193, 0, v193
	v_max_f32_e32 v194, 0, v194
	v_max_f32_e32 v195, 0, v195
	v_max_f32_e32 v196, 0, v196
	v_max_f32_e32 v197, 0, v197
	s_waitcnt lgkmcnt(3)
	v_mfma_f32_32x32x16_f16 v[2:17], v[38:41], v[170:173], v[2:17]
	v_max_f32_e32 v222, 0, v222
	v_max_f32_e32 v223, 0, v223
	v_max_f32_e32 v224, 0, v224
	v_max_f32_e32 v225, 0, v225
	v_max_f32_e32 v226, 0, v226
	v_max_f32_e32 v227, 0, v227
	v_max_f32_e32 v228, 0, v228
	v_max_f32_e32 v229, 0, v229
	v_mfma_f32_32x32x16_f16 v[18:33], v[46:49], v[170:173], v[18:33]
	ds_read_b128 v[170:173], v69 offset:1952
	v_max_f32_e32 v230, 0, v230
	v_max_f32_e32 v231, 0, v231
	v_max_f32_e32 v232, 0, v232
	v_max_f32_e32 v233, 0, v233
	v_max_f32_e32 v234, 0, v234
	v_max_f32_e32 v235, 0, v235
	v_max_f32_e32 v236, 0, v236
	v_max_f32_e32 v237, 0, v237
	s_waitcnt lgkmcnt(3)
	v_mfma_f32_32x32x16_f16 v[2:17], v[50:53], v[174:177], v[2:17]
	v_fmac_f32_e32 v108, v251, v182
	v_fmac_f32_e32 v109, v251, v183
	v_fmac_f32_e32 v110, v251, v184
	v_fmac_f32_e32 v111, v251, v185
	v_fmac_f32_e32 v104, v251, v186
	v_fmac_f32_e32 v105, v251, v187
	v_fmac_f32_e32 v106, v251, v188
	v_fmac_f32_e32 v107, v251, v189
	v_mfma_f32_32x32x16_f16 v[18:33], v[58:61], v[174:177], v[18:33]
	ds_read_b128 v[174:177], v69 offset:1984
	v_fmac_f32_e32 v100, v251, v190
	v_fmac_f32_e32 v101, v251, v191
	v_fmac_f32_e32 v102, v251, v192
	v_fmac_f32_e32 v103, v251, v193
	v_fmac_f32_e32 v98, v251, v194
	v_fmac_f32_e32 v99, v251, v195
	v_fmac_f32_e32 v84, v251, v196
	v_fmac_f32_e32 v85, v251, v197
	s_waitcnt lgkmcnt(3)
	v_mfma_f32_32x32x16_f16 v[2:17], v[54:57], v[178:181], v[2:17]
	v_fmac_f32_e32 v94, v251, v222
	v_fmac_f32_e32 v95, v251, v223
	v_fmac_f32_e32 v96, v251, v224
	v_fmac_f32_e32 v97, v251, v225
	v_fmac_f32_e32 v90, v251, v226
	v_fmac_f32_e32 v91, v251, v227
	v_fmac_f32_e32 v92, v251, v228
	v_fmac_f32_e32 v93, v251, v229
	v_mfma_f32_32x32x16_f16 v[18:33], v[62:65], v[178:181], v[18:33]
	ds_read_b128 v[178:181], v69 offset:2016
	v_fmac_f32_e32 v86, v251, v230
	v_fmac_f32_e32 v87, v251, v231
	v_fmac_f32_e32 v88, v251, v232
	v_fmac_f32_e32 v89, v251, v233
	v_fmac_f32_e32 v82, v251, v234
	v_fmac_f32_e32 v83, v251, v235
	v_fmac_f32_e32 v78, v251, v236
	v_fmac_f32_e32 v79, v251, v237
	s_waitcnt lgkmcnt(3)
	v_mfma_f32_32x32x16_f16 v[182:197], v[34:37], v[166:169], 0
	s_nop 1
	v_max_f32_e32 v2, 0, v2
	v_max_f32_e32 v3, 0, v3
	v_max_f32_e32 v4, 0, v4
	v_max_f32_e32 v5, 0, v5
	v_max_f32_e32 v6, 0, v6
	v_max_f32_e32 v7, 0, v7
	v_max_f32_e32 v8, 0, v8
	v_max_f32_e32 v9, 0, v9
	v_mfma_f32_32x32x16_f16 v[222:237], v[42:45], v[166:169], 0
	v_max_f32_e32 v10, 0, v10
	v_max_f32_e32 v11, 0, v11
	v_max_f32_e32 v12, 0, v12
	v_max_f32_e32 v13, 0, v13
	v_max_f32_e32 v14, 0, v14
	v_max_f32_e32 v15, 0, v15
	v_max_f32_e32 v16, 0, v16
	v_max_f32_e32 v17, 0, v17
	s_waitcnt lgkmcnt(2)
	v_mfma_f32_32x32x16_f16 v[182:197], v[38:41], v[170:173], v[182:197]
	v_max_f32_e32 v18, 0, v18
	v_max_f32_e32 v19, 0, v19
	v_max_f32_e32 v20, 0, v20
	v_max_f32_e32 v21, 0, v21
	v_max_f32_e32 v22, 0, v22
	v_max_f32_e32 v23, 0, v23
	v_max_f32_e32 v24, 0, v24
	v_max_f32_e32 v25, 0, v25
	v_mfma_f32_32x32x16_f16 v[222:237], v[46:49], v[170:173], v[222:237]
	v_max_f32_e32 v26, 0, v26
	v_max_f32_e32 v27, 0, v27
	v_max_f32_e32 v28, 0, v28
	v_max_f32_e32 v29, 0, v29
	v_max_f32_e32 v30, 0, v30
	v_max_f32_e32 v31, 0, v31
	v_max_f32_e32 v32, 0, v32
	v_max_f32_e32 v33, 0, v33
	s_waitcnt lgkmcnt(1)
	v_mfma_f32_32x32x16_f16 v[182:197], v[50:53], v[174:177], v[182:197]
	v_fmac_f32_e32 v108, v252, v2
	v_fmac_f32_e32 v109, v252, v3
	v_fmac_f32_e32 v110, v252, v4
	v_fmac_f32_e32 v111, v252, v5
	v_fmac_f32_e32 v104, v252, v6
	v_fmac_f32_e32 v105, v252, v7
	v_fmac_f32_e32 v106, v252, v8
	v_fmac_f32_e32 v107, v252, v9
	v_mfma_f32_32x32x16_f16 v[222:237], v[58:61], v[174:177], v[222:237]
	v_fmac_f32_e32 v100, v252, v10
	v_fmac_f32_e32 v101, v252, v11
	v_fmac_f32_e32 v102, v252, v12
	v_fmac_f32_e32 v103, v252, v13
	v_fmac_f32_e32 v98, v252, v14
	v_fmac_f32_e32 v99, v252, v15
	v_fmac_f32_e32 v84, v252, v16
	v_fmac_f32_e32 v85, v252, v17
	s_waitcnt lgkmcnt(0)
	v_mfma_f32_32x32x16_f16 v[182:197], v[54:57], v[178:181], v[182:197]
	v_fmac_f32_e32 v94, v252, v18
	v_fmac_f32_e32 v95, v252, v19
	v_fmac_f32_e32 v96, v252, v20
	v_fmac_f32_e32 v97, v252, v21
	v_fmac_f32_e32 v90, v252, v22
	v_fmac_f32_e32 v91, v252, v23
	v_fmac_f32_e32 v92, v252, v24
	v_fmac_f32_e32 v93, v252, v25
	v_mfma_f32_32x32x16_f16 v[222:237], v[62:65], v[178:181], v[222:237]
	v_fmac_f32_e32 v86, v252, v26
	v_fmac_f32_e32 v87, v252, v27
	v_fmac_f32_e32 v88, v252, v28
	v_fmac_f32_e32 v89, v252, v29
	v_fmac_f32_e32 v82, v252, v30
	v_fmac_f32_e32 v83, v252, v31
	v_fmac_f32_e32 v78, v252, v32
	v_fmac_f32_e32 v79, v252, v33
	s_setprio 0
	s_nop 9
	v_max_f32_e32 v182, 0, v182
	v_max_f32_e32 v183, 0, v183
	v_max_f32_e32 v184, 0, v184
	v_max_f32_e32 v185, 0, v185
	v_max_f32_e32 v186, 0, v186
	v_max_f32_e32 v187, 0, v187
	v_max_f32_e32 v188, 0, v188
	v_max_f32_e32 v189, 0, v189
	v_max_f32_e32 v190, 0, v190
	v_max_f32_e32 v191, 0, v191
	v_max_f32_e32 v192, 0, v192
	v_max_f32_e32 v193, 0, v193
	v_max_f32_e32 v194, 0, v194
	v_max_f32_e32 v195, 0, v195
	v_max_f32_e32 v196, 0, v196
	v_max_f32_e32 v197, 0, v197
	v_max_f32_e32 v222, 0, v222
	v_max_f32_e32 v223, 0, v223
	v_max_f32_e32 v224, 0, v224
	v_max_f32_e32 v225, 0, v225
	v_max_f32_e32 v226, 0, v226
	v_max_f32_e32 v227, 0, v227
	v_max_f32_e32 v228, 0, v228
	v_max_f32_e32 v229, 0, v229
	v_max_f32_e32 v230, 0, v230
	v_max_f32_e32 v231, 0, v231
	v_max_f32_e32 v232, 0, v232
	v_max_f32_e32 v233, 0, v233
	v_max_f32_e32 v234, 0, v234
	v_max_f32_e32 v235, 0, v235
	v_max_f32_e32 v236, 0, v236
	v_max_f32_e32 v237, 0, v237
	v_fmac_f32_e32 v108, v253, v182
	v_fmac_f32_e32 v109, v253, v183
	v_fmac_f32_e32 v110, v253, v184
	v_fmac_f32_e32 v111, v253, v185
	v_fmac_f32_e32 v104, v253, v186
	v_fmac_f32_e32 v105, v253, v187
	v_fmac_f32_e32 v106, v253, v188
	v_fmac_f32_e32 v107, v253, v189
	v_fmac_f32_e32 v100, v253, v190
	v_fmac_f32_e32 v101, v253, v191
	v_fmac_f32_e32 v102, v253, v192
	v_fmac_f32_e32 v103, v253, v193
	v_fmac_f32_e32 v98, v253, v194
	v_fmac_f32_e32 v99, v253, v195
	v_fmac_f32_e32 v84, v253, v196
	v_fmac_f32_e32 v85, v253, v197
	v_fmac_f32_e32 v94, v253, v222
	v_fmac_f32_e32 v95, v253, v223
	v_fmac_f32_e32 v96, v253, v224
	v_fmac_f32_e32 v97, v253, v225
	v_fmac_f32_e32 v90, v253, v226
	v_fmac_f32_e32 v91, v253, v227
	v_fmac_f32_e32 v92, v253, v228
	v_fmac_f32_e32 v93, v253, v229
	v_fmac_f32_e32 v86, v253, v230
	v_fmac_f32_e32 v87, v253, v231
	v_fmac_f32_e32 v88, v253, v232
	v_fmac_f32_e32 v89, v253, v233
	v_fmac_f32_e32 v82, v253, v234
	v_fmac_f32_e32 v83, v253, v235
	v_fmac_f32_e32 v78, v253, v236
	v_fmac_f32_e32 v79, v253, v237
	v_ashrrev_i32_e32 v81, 31, v80
	v_lshl_add_u64 v[2:3], v[80:81], 2, v[76:77]
	v_pk_add_f32 v[4:5], v[108:109], 0 op_sel_hi:[1,0]
	v_pk_add_f32 v[6:7], v[110:111], 0 op_sel_hi:[1,0]
	global_store_dwordx4 v[2:3], v[4:7], off
	v_lshlrev_b32_e32 v8, 1, v149
	v_cmp_gt_i32_e64 s[8:9], s21, v8
	v_pk_add_f32 v[4:5], v[104:105], 0 op_sel_hi:[1,0]
	v_pk_add_f32 v[6:7], v[106:107], 0 op_sel_hi:[1,0]
	global_store_dwordx4 v[2:3], v[4:7], off offset:32
	s_nop 1
	v_pk_add_f32 v[4:5], v[100:101], 0 op_sel_hi:[1,0]
	v_pk_add_f32 v[6:7], v[102:103], 0 op_sel_hi:[1,0]
	global_store_dwordx4 v[2:3], v[4:7], off offset:64
	s_nop 1
	v_pk_add_f32 v[4:5], v[98:99], 0 op_sel_hi:[1,0]
	v_pk_add_f32 v[6:7], v[84:85], 0 op_sel_hi:[1,0]
	global_store_dwordx4 v[2:3], v[4:7], off offset:96
	s_and_saveexec_b64 s[10:11], s[8:9]
	s_cbranch_execz .LBB0_613
	v_pk_add_f32 v[4:5], v[94:95], 0 op_sel_hi:[1,0]
	v_pk_add_f32 v[6:7], v[96:97], 0 op_sel_hi:[1,0]
	global_store_dwordx4 v[2:3], v[4:7], off offset:128
	s_nop 1
	v_pk_add_f32 v[4:5], v[90:91], 0 op_sel_hi:[1,0]
	v_pk_add_f32 v[6:7], v[92:93], 0 op_sel_hi:[1,0]
	global_store_dwordx4 v[2:3], v[4:7], off offset:160
	s_nop 1
	v_pk_add_f32 v[4:5], v[86:87], 0 op_sel_hi:[1,0]
	v_pk_add_f32 v[6:7], v[88:89], 0 op_sel_hi:[1,0]
	global_store_dwordx4 v[2:3], v[4:7], off offset:192
	s_nop 1
	v_pk_add_f32 v[4:5], v[82:83], 0 op_sel_hi:[1,0]
	v_pk_add_f32 v[6:7], v[78:79], 0 op_sel_hi:[1,0]
	global_store_dwordx4 v[2:3], v[4:7], off offset:224
	s_branch .LBB0_613
